# permlane32_swap max exchange extended to the NSA (E5) tile loops and compressed pass (17 sites total)
# speedup vs baseline: 1.0035x; 1.0035x over previous
.LBB0_883:
	s_add_i32 s39, s41, 1
	v_mov_b32_e32 v36, v2
	s_waitcnt vmcnt(3)
	v_mov_b64_e32 v[2:3], v[50:51]
	s_cmp_lt_u32 s41, s15
	v_mov_b64_e32 v[4:5], v[52:53]
	s_cselect_b32 s41, s2, 0
	v_or_b32_e32 v6, s41, v93
	v_ashrrev_i32_e32 v7, 31, v6
	v_lshlrev_b64 v[6:7], 7, v[6:7]
	s_waitcnt vmcnt(0)
	v_mov_b64_e32 v[24:25], v[62:63]
	v_mov_b64_e32 v[28:29], v[58:59]
	v_mov_b64_e32 v[32:33], v[54:55]
	v_lshl_add_u64 v[6:7], v[82:83], 0, v[6:7]
	v_mov_b64_e32 v[26:27], v[64:65]
	v_mov_b64_e32 v[30:31], v[60:61]
	v_mov_b64_e32 v[34:35], v[56:57]
	global_load_dwordx4 v[50:53], v[6:7], off
	global_load_dwordx4 v[54:57], v[6:7], off offset:16
	global_load_dwordx4 v[58:61], v[6:7], off offset:32
	global_load_dwordx4 v[62:65], v[6:7], off offset:48
	s_setprio 1
	v_mfma_f32_32x32x16_bf16 v[2:17], v[2:5], v[130:133], 0
	s_add_i32 s2, s2, 32
	s_mov_b32 s41, s39
	v_mfma_f32_32x32x16_bf16 v[2:17], v[32:35], v[134:137], v[2:17]
	v_mfma_f32_32x32x16_bf16 v[2:17], v[28:31], v[138:141], v[2:17]
	v_mfma_f32_32x32x16_bf16 v[2:17], v[24:27], v[142:145], v[2:17]
	v_add_u32_e32 v24, s3, v20
	v_cmp_le_i32_e32 vcc, v24, v22
	v_add_u32_e32 v25, 16, v24
	v_add_u32_e32 v26, 32, v24
	s_addk_i32 s3, 0x200
	s_cmp_eq_u32 s38, s3
	s_nop 5
	v_mul_f32_e32 v2, 0x3e38aa3b, v2
	v_cndmask_b32_e32 v2, v220, v2, vcc
	v_mul_f32_e32 v3, 0x3e38aa3b, v3
	v_cmp_le_i32_e32 vcc, v25, v22
	v_mul_f32_e32 v4, 0x3e38aa3b, v4
	v_mul_f32_e32 v5, 0x3e38aa3b, v5
	v_cndmask_b32_e32 v3, v220, v3, vcc
	v_cmp_le_i32_e32 vcc, v26, v22
	v_add_u32_e32 v26, 48, v24
	v_mul_f32_e32 v6, 0x3e38aa3b, v6
	v_cndmask_b32_e32 v4, v220, v4, vcc
	v_cmp_le_i32_e32 vcc, v26, v22
	v_add_u32_e32 v26, 64, v24
	v_mul_f32_e32 v7, 0x3e38aa3b, v7
	v_cndmask_b32_e32 v5, v220, v5, vcc
	v_cmp_le_i32_e32 vcc, v26, v22
	v_add_u32_e32 v26, 0x50, v24
	v_mul_f32_e32 v8, 0x3e38aa3b, v8
	v_cndmask_b32_e32 v6, v220, v6, vcc
	v_cmp_le_i32_e32 vcc, v26, v22
	v_add_u32_e32 v26, 0x60, v24
	v_mul_f32_e32 v9, 0x3e38aa3b, v9
	v_cndmask_b32_e32 v7, v220, v7, vcc
	v_cmp_le_i32_e32 vcc, v26, v22
	v_add_u32_e32 v26, 0x70, v24
	v_mul_f32_e32 v10, 0x3e38aa3b, v10
	v_cndmask_b32_e32 v8, v220, v8, vcc
	v_cmp_le_i32_e32 vcc, v26, v22
	v_add_u32_e32 v26, 0x100, v24
	v_mul_f32_e32 v11, 0x3e38aa3b, v11
	v_cndmask_b32_e32 v9, v220, v9, vcc
	v_cmp_le_i32_e32 vcc, v26, v22
	v_add_u32_e32 v26, 0x110, v24
	v_max3_f32 v25, v2, s85, v3
	v_cndmask_b32_e32 v10, v220, v10, vcc
	v_cmp_le_i32_e32 vcc, v26, v22
	v_add_u32_e32 v26, 0x120, v24
	v_mul_f32_e32 v12, 0x3e38aa3b, v12
	v_cndmask_b32_e32 v11, v220, v11, vcc
	v_cmp_le_i32_e32 vcc, v26, v22
	v_add_u32_e32 v26, 0x130, v24
	v_max3_f32 v25, v25, v4, v5
	v_cndmask_b32_e32 v12, v220, v12, vcc
	v_mul_f32_e32 v13, 0x3e38aa3b, v13
	v_cmp_le_i32_e32 vcc, v26, v22
	v_add_u32_e32 v26, 0x140, v24
	v_max3_f32 v25, v25, v6, v7
	v_cndmask_b32_e32 v13, v220, v13, vcc
	v_mul_f32_e32 v14, 0x3e38aa3b, v14
	v_cmp_le_i32_e32 vcc, v26, v22
	v_add_u32_e32 v26, 0x150, v24
	v_max3_f32 v25, v25, v8, v9
	v_cndmask_b32_e32 v14, v220, v14, vcc
	v_mul_f32_e32 v15, 0x3e38aa3b, v15
	v_cmp_le_i32_e32 vcc, v26, v22
	v_add_u32_e32 v26, 0x160, v24
	v_max3_f32 v25, v25, v10, v11
	v_cndmask_b32_e32 v15, v220, v15, vcc
	v_mul_f32_e32 v16, 0x3e38aa3b, v16
	v_cmp_le_i32_e32 vcc, v26, v22
	v_add_u32_e32 v24, 0x170, v24
	v_max3_f32 v25, v25, v12, v13
	v_cndmask_b32_e32 v16, v220, v16, vcc
	v_mul_f32_e32 v17, 0x3e38aa3b, v17
	v_cmp_le_i32_e32 vcc, v24, v22
	v_max3_f32 v25, v25, v14, v15
	s_nop 0
	v_cndmask_b32_e32 v17, v220, v17, vcc
	v_max3_f32 v24, v25, v16, v17
	v_mov_b32_e32 v25, v24
	s_nop 1
	v_permlane32_swap_b32_e32 v25, v24
	s_waitcnt lgkmcnt(0)
	v_max3_f32 v24, v23, v24, v25
	v_cmp_neq_f32_e32 vcc, s85, v24
	s_nop 1
	v_cndmask_b32_e32 v96, 0, v24, vcc
	v_sub_f32_e32 v2, v2, v96
	v_exp_f32_e32 v2, v2
	v_sub_f32_e32 v3, v3, v96
	v_exp_f32_e32 v3, v3
	v_sub_f32_e32 v23, v23, v96
	v_add_f32_e32 v2, 0, v2
	v_add_f32_e32 v2, v3, v2
	v_sub_f32_e32 v3, v4, v96
	v_exp_f32_e32 v3, v3
	s_nop 0
	v_add_f32_e32 v2, v3, v2
	v_sub_f32_e32 v3, v5, v96
	v_exp_f32_e32 v3, v3
	s_nop 0
	v_add_f32_e32 v2, v3, v2
	v_sub_f32_e32 v3, v6, v96
	v_exp_f32_e32 v3, v3
	s_nop 0
	v_add_f32_e32 v2, v3, v2
	v_sub_f32_e32 v3, v7, v96
	v_exp_f32_e32 v3, v3
	s_nop 0
	v_add_f32_e32 v2, v3, v2
	v_sub_f32_e32 v3, v8, v96
	v_exp_f32_e32 v3, v3
	s_nop 0
	v_add_f32_e32 v2, v3, v2
	v_sub_f32_e32 v3, v9, v96
	v_exp_f32_e32 v3, v3
	s_nop 0
	v_add_f32_e32 v2, v3, v2
	v_sub_f32_e32 v3, v10, v96
	v_exp_f32_e32 v3, v3
	s_nop 0
	v_add_f32_e32 v2, v3, v2
	v_sub_f32_e32 v3, v11, v96
	v_exp_f32_e32 v3, v3
	s_nop 0
	v_add_f32_e32 v2, v3, v2
	v_sub_f32_e32 v3, v12, v96
	v_exp_f32_e32 v3, v3
	s_nop 0
	v_add_f32_e32 v2, v3, v2
	v_sub_f32_e32 v3, v13, v96
	v_exp_f32_e32 v3, v3
	s_nop 0
	v_add_f32_e32 v2, v3, v2
	v_sub_f32_e32 v3, v14, v96
	v_exp_f32_e32 v3, v3
	s_nop 0
	v_add_f32_e32 v2, v3, v2
	v_sub_f32_e32 v3, v15, v96
	v_exp_f32_e32 v3, v3
	s_nop 0
	v_add_f32_e32 v2, v3, v2
	v_sub_f32_e32 v3, v16, v96
	v_exp_f32_e32 v3, v3
	s_nop 0
	v_add_f32_e32 v2, v3, v2
	v_sub_f32_e32 v3, v17, v96
	v_exp_f32_e32 v3, v3
	s_nop 0
	v_add_f32_e32 v2, v3, v2
	v_exp_f32_e32 v3, v23
	v_mov_b32_e32 v23, v24
	v_fmac_f32_e32 v2, v36, v3
	s_cbranch_scc0 .LBB0_883
	ds_bpermute_b32 v3, v167, v2
	v_lshlrev_b32_e32 v166, 3, v21
	v_add_u32_e32 v98, 0x18f, v20
	v_lshl_or_b32 v84, v92, 8, v223
	v_mov_b32_e32 v85, v1
	s_waitcnt lgkmcnt(0)
	v_add_f32_e32 v3, v2, v3
	v_div_scale_f32 v4, s[2:3], v3, v3, 1.0
	v_rcp_f32_e32 v5, v4
	v_div_scale_f32 v6, vcc, 1.0, v3, 1.0
	s_add_u32 s2, s18, s22
	v_fma_f32 v7, -v4, v5, 1.0
	v_fmac_f32_e32 v5, v7, v5
	v_mul_f32_e32 v7, v6, v5
	v_fma_f32 v8, -v4, v7, v6
	v_fmac_f32_e32 v7, v8, v5
	v_fma_f32 v4, -v4, v7, v6
	v_div_fmas_f32 v4, v4, v5, v7
	v_div_fixup_f32 v4, v4, v3, 1.0
	v_cmp_lt_f32_e32 vcc, 0, v3
	v_lshlrev_b32_e32 v3, 12, v18
	v_mov_b32_e32 v2, 0
	v_cndmask_b32_e32 v97, 0, v4, vcc
	v_lshlrev_b32_e32 v4, 7, v91
	v_or3_b32 v99, v3, v4, v166
	v_and_b32_e32 v4, 16, v19
	v_mov_b32_e32 v5, v1
	s_addc_u32 s3, s19, s23
	v_lshl_add_u64 v[86:87], s[2:3], 0, v[4:5]
	v_lshlrev_b32_e32 v88, 8, v91
	v_mov_b32_e32 v89, v1
	s_mov_b32 s22, 0
	v_mov_b32_e32 v3, v2
	v_mov_b32_e32 v4, v2
	v_mov_b32_e32 v5, v2
	v_mov_b32_e32 v6, v2
	v_mov_b32_e32 v7, v2
	v_mov_b32_e32 v8, v2
	v_mov_b32_e32 v9, v2
	v_mov_b32_e32 v10, v2
	v_mov_b32_e32 v11, v2
	v_mov_b32_e32 v12, v2
	v_mov_b32_e32 v13, v2
	v_mov_b32_e32 v14, v2
	v_mov_b32_e32 v15, v2
	v_mov_b32_e32 v16, v2
	v_mov_b32_e32 v17, v2
	v_mov_b32_e32 v18, v2
	v_mov_b32_e32 v19, v2
	v_mov_b32_e32 v20, v2
	v_mov_b32_e32 v21, v2
	v_mov_b32_e32 v22, v2
	v_mov_b32_e32 v23, v2
	v_mov_b32_e32 v24, v2
	v_mov_b32_e32 v25, v2
	v_mov_b32_e32 v26, v2
	v_mov_b32_e32 v27, v2
	v_mov_b32_e32 v28, v2
	v_mov_b32_e32 v29, v2
	v_mov_b32_e32 v30, v2
	v_mov_b32_e32 v31, v2
	v_mov_b32_e32 v32, v2
	v_mov_b32_e32 v33, v2
	s_branch .LBB0_886

.LBB0_924:
	s_mulk_i32 s23, 0x4800
	s_cmp_lt_i32 s76, 2
	s_mov_b64 s[2:3], -1
	s_cbranch_scc1 .LBB0_934
	s_cmp_gt_i32 s76, 2
	s_cbranch_scc0 .LBB0_929
	v_add3_u32 v74, s23, v170, v173
	s_setprio 1
	ds_read_b128 v[66:69], v74
	ds_read_b128 v[70:73], v74 offset:16
	v_add_f32_e32 v84, 0x40c00000, v189
	v_mov_b32_e32 v190, v189
	v_mov_b32_e32 v191, v188
	s_waitcnt lgkmcnt(1)
	v_mfma_f32_32x32x16_bf16 v[114:129], v[66:69], v[130:133], 0
	s_waitcnt lgkmcnt(0)
	v_mfma_f32_32x32x16_bf16 v[114:129], v[70:73], v[134:137], v[114:129]
	ds_read_b128 v[66:69], v74 offset:32
	ds_read_b128 v[70:73], v74 offset:48
	s_waitcnt lgkmcnt(1)
	v_mfma_f32_32x32x16_bf16 v[114:129], v[66:69], v[138:141], v[114:129]
	s_waitcnt lgkmcnt(0)
	v_mfma_f32_32x32x16_bf16 v[114:129], v[70:73], v[142:145], v[114:129]
	ds_read_b128 v[66:69], v74 offset:4608
	ds_read_b128 v[70:73], v74 offset:4624
	s_waitcnt lgkmcnt(1)
	v_mfma_f32_32x32x16_bf16 v[98:113], v[66:69], v[130:133], 0
	s_waitcnt lgkmcnt(0)
	v_mfma_f32_32x32x16_bf16 v[98:113], v[70:73], v[134:137], v[98:113]
	ds_read_b128 v[66:69], v74 offset:4640
	ds_read_b128 v[70:73], v74 offset:4656
	s_nop 3
	v_max3_f32 v74, v114, s85, v115
	s_waitcnt lgkmcnt(1)
	v_mfma_f32_32x32x16_bf16 v[98:113], v[66:69], v[138:141], v[98:113]
	v_max3_f32 v66, v74, v116, v117
	v_max3_f32 v66, v66, v118, v119
	v_max3_f32 v66, v66, v120, v121
	v_max3_f32 v66, v66, v122, v123
	v_max3_f32 v66, v66, v124, v125
	v_max3_f32 v66, v66, v126, v127
	v_max3_f32 v66, v66, v128, v129
	s_waitcnt lgkmcnt(0)
	v_mfma_f32_32x32x16_bf16 v[98:113], v[70:73], v[142:145], v[98:113]
	s_nop 11
	v_max3_f32 v66, v66, v98, v99
	v_max3_f32 v66, v66, v100, v101
	v_max3_f32 v66, v66, v102, v103
	v_max3_f32 v66, v66, v104, v105
	v_max3_f32 v66, v66, v106, v107
	v_max3_f32 v66, v66, v108, v109
	v_max3_f32 v66, v66, v110, v111
	v_max3_f32 v82, v66, v112, v113
	v_mov_b32_e32 v83, v82
	s_nop 1
	v_permlane32_swap_b32_e32 v83, v82
	v_mov_b64_e32 v[80:81], v[48:49]
	v_mov_b64_e32 v[78:79], v[46:47]
	v_mov_b64_e32 v[76:77], v[44:45]
	v_mov_b64_e32 v[74:75], v[42:43]
	s_waitcnt lgkmcnt(0)
	v_max_f32_e32 v83, v83, v83
	v_max_f32_e32 v82, v82, v83
	v_mul_f32_e32 v82, 0x3e38aa3b, v82
	v_cndmask_b32_e64 v192, v220, v82, s[38:39]
	v_cmp_gt_f32_e32 vcc, v192, v84
	v_mov_b64_e32 v[96:97], v[64:65]
	v_mov_b64_e32 v[72:73], v[40:41]
	v_mov_b64_e32 v[70:71], v[38:39]
	v_mov_b64_e32 v[68:69], v[36:37]
	v_mov_b64_e32 v[66:67], v[34:35]
	v_mov_b64_e32 v[94:95], v[62:63]
	v_mov_b64_e32 v[92:93], v[60:61]
	v_mov_b64_e32 v[90:91], v[58:59]
	v_mov_b64_e32 v[88:89], v[56:57]
	v_mov_b64_e32 v[86:87], v[54:55]
	v_mov_b64_e32 v[84:85], v[52:53]
	v_mov_b64_e32 v[82:83], v[50:51]
	s_cbranch_vccz .LBB0_928
	v_cndmask_b32_e32 v190, v189, v192, vcc
	v_sub_f32_e32 v66, v189, v190
	v_exp_f32_e32 v66, v66
	s_nop 0
	v_cndmask_b32_e32 v82, 1.0, v66, vcc
	v_mul_f32_e32 v191, v188, v82
	v_pk_mul_f32 v[80:81], v[48:49], v[82:83] op_sel_hi:[1,0]
	v_pk_mul_f32 v[78:79], v[46:47], v[82:83] op_sel_hi:[1,0]
	v_pk_mul_f32 v[76:77], v[44:45], v[82:83] op_sel_hi:[1,0]
	v_pk_mul_f32 v[74:75], v[42:43], v[82:83] op_sel_hi:[1,0]
	v_pk_mul_f32 v[72:73], v[40:41], v[82:83] op_sel_hi:[1,0]
	v_pk_mul_f32 v[70:71], v[38:39], v[82:83] op_sel_hi:[1,0]
	v_pk_mul_f32 v[68:69], v[36:37], v[82:83] op_sel_hi:[1,0]
	v_pk_mul_f32 v[66:67], v[34:35], v[82:83] op_sel_hi:[1,0]
	v_pk_mul_f32 v[96:97], v[64:65], v[82:83] op_sel_hi:[1,0]
	v_pk_mul_f32 v[94:95], v[62:63], v[82:83] op_sel_hi:[1,0]
	v_pk_mul_f32 v[92:93], v[60:61], v[82:83] op_sel_hi:[1,0]
	v_pk_mul_f32 v[90:91], v[58:59], v[82:83] op_sel_hi:[1,0]
	v_pk_mul_f32 v[88:89], v[56:57], v[82:83] op_sel_hi:[1,0]
	v_pk_mul_f32 v[86:87], v[54:55], v[82:83] op_sel_hi:[1,0]
	v_pk_mul_f32 v[84:85], v[52:53], v[82:83] op_sel_hi:[1,0]
	v_pk_mul_f32 v[82:83], v[50:51], v[82:83] op_sel_hi:[1,0]

.LBB0_929:
	s_and_b64 vcc, exec, s[2:3]
	s_cbranch_vccz .LBB0_933
	s_nop 0
	v_add3_u32 v78, s23, v170, v173
	s_setprio 1
	ds_read_b128 v[66:69], v78
	ds_read_b128 v[70:73], v78 offset:16
	v_cmp_lt_i32_e32 vcc, -1, v187
	v_cmp_gt_i32_e64 s[38:39], 1, v187
	v_cmp_gt_i32_e64 s[40:41], 32, v187
	s_waitcnt lgkmcnt(1)
	v_mfma_f32_32x32x16_bf16 v[98:113], v[66:69], v[130:133], 0
	v_cmp_gt_i32_e64 s[42:43], 33, v187
	v_cmp_gt_i32_e64 s[44:45], 34, v187
	v_cmp_gt_i32_e64 s[46:47], 35, v187
	v_cmp_gt_i32_e64 s[48:49], 36, v187
	v_cmp_gt_i32_e64 s[50:51], 37, v187
	v_cmp_gt_i32_e64 s[52:53], 38, v187
	v_cmp_gt_i32_e64 s[56:57], 39, v187
	s_waitcnt lgkmcnt(0)
	v_mfma_f32_32x32x16_bf16 v[98:113], v[70:73], v[134:137], v[98:113]
	ds_read_b128 v[66:69], v78 offset:32
	ds_read_b128 v[70:73], v78 offset:48
	v_cmp_gt_i32_e64 s[58:59], 48, v187
	v_cmp_gt_i32_e64 s[60:61], 49, v187
	v_cmp_gt_i32_e64 s[62:63], 50, v187
	v_cmp_gt_i32_e64 s[64:65], 51, v187
	v_cmp_gt_i32_e64 s[66:67], 52, v187
	v_cmp_gt_i32_e64 s[68:69], 53, v187
	s_waitcnt lgkmcnt(1)
	v_mfma_f32_32x32x16_bf16 v[98:113], v[66:69], v[138:141], v[98:113]
	ds_read_b128 v[66:69], v78 offset:4608
	ds_read_b128 v[74:77], v78 offset:4624
	v_cmp_gt_i32_e64 s[70:71], 54, v187
	v_cmp_gt_i32_e64 s[54:55], 55, v187
	v_mov_b64_e32 v[96:97], v[64:65]
	v_mov_b32_e32 v190, v189
	v_mov_b64_e32 v[94:95], v[62:63]
	v_mov_b64_e32 v[92:93], v[60:61]
	s_waitcnt lgkmcnt(1)
	v_mfma_f32_32x32x16_bf16 v[114:129], v[66:69], v[130:133], 0
	ds_read_b128 v[66:69], v78 offset:4640
	ds_read_b128 v[78:81], v78 offset:4656
	v_mov_b64_e32 v[90:91], v[58:59]
	v_mov_b64_e32 v[88:89], v[56:57]
	v_mov_b64_e32 v[86:87], v[54:55]
	v_mov_b64_e32 v[84:85], v[52:53]
	v_mov_b64_e32 v[82:83], v[50:51]
	s_waitcnt lgkmcnt(2)
	v_mfma_f32_32x32x16_bf16 v[114:129], v[74:77], v[134:137], v[114:129]
	v_mfma_f32_32x32x16_bf16 v[98:113], v[70:73], v[142:145], v[98:113]
	s_waitcnt lgkmcnt(1)
	v_mfma_f32_32x32x16_bf16 v[114:129], v[66:69], v[138:141], v[114:129]
	s_nop 9
	v_cndmask_b32_e32 v195, v220, v98, vcc
	v_cmp_lt_i32_e32 vcc, 1, v187
	v_cndmask_b32_e64 v191, v99, v220, s[38:39]
	v_max3_f32 v70, v195, s85, v191
	v_cndmask_b32_e32 v192, v220, v100, vcc
	v_cmp_lt_i32_e32 vcc, 2, v187
	v_mov_b32_e32 v99, v188
	s_waitcnt lgkmcnt(0)
	v_mfma_f32_32x32x16_bf16 v[114:129], v[78:81], v[142:145], v[114:129]
	v_cndmask_b32_e32 v193, v220, v101, vcc
	v_cmp_lt_i32_e32 vcc, 3, v187
	v_max3_f32 v70, v70, v192, v193
	s_nop 0
	v_cndmask_b32_e32 v194, v220, v102, vcc
	v_cmp_lt_i32_e32 vcc, 4, v187
	s_nop 5
	v_cndmask_b32_e64 v196, v115, v220, s[42:43]
	v_cndmask_b32_e32 v101, v220, v103, vcc
	v_cmp_lt_i32_e32 vcc, 5, v187
	v_max3_f32 v70, v70, v194, v101
	v_cndmask_b32_e64 v197, v116, v220, s[44:45]
	v_cndmask_b32_e32 v102, v220, v104, vcc
	v_cmp_lt_i32_e32 vcc, 6, v187
	v_cndmask_b32_e64 v198, v117, v220, s[46:47]
	v_cndmask_b32_e64 v199, v118, v220, s[48:49]
	v_cndmask_b32_e32 v103, v220, v105, vcc
	v_cmp_lt_i32_e32 vcc, 15, v187
	v_max3_f32 v70, v70, v102, v103
	v_cndmask_b32_e64 v200, v119, v220, s[50:51]
	v_cndmask_b32_e32 v105, v220, v106, vcc
	v_cmp_lt_i32_e32 vcc, 16, v187
	v_cndmask_b32_e64 v202, v120, v220, s[52:53]
	v_cndmask_b32_e64 v203, v121, v220, s[56:57]
	v_cndmask_b32_e32 v104, v220, v107, vcc
	v_cmp_lt_i32_e32 vcc, 17, v187
	v_max3_f32 v70, v70, v105, v104
	v_cndmask_b32_e64 v204, v122, v220, s[58:59]
	v_cndmask_b32_e32 v106, v220, v108, vcc
	v_cmp_lt_i32_e32 vcc, 18, v187
	v_cndmask_b32_e64 v205, v123, v220, s[60:61]
	v_cndmask_b32_e64 v226, v124, v220, s[62:63]
	v_cndmask_b32_e32 v107, v220, v109, vcc
	v_cmp_lt_i32_e32 vcc, 19, v187
	v_max3_f32 v70, v70, v106, v107
	v_cndmask_b32_e64 v227, v125, v220, s[64:65]
	v_cndmask_b32_e32 v108, v220, v110, vcc
	v_cmp_lt_i32_e32 vcc, 20, v187
	v_cndmask_b32_e64 v228, v126, v220, s[66:67]
	v_cndmask_b32_e64 v229, v127, v220, s[68:69]
	v_cndmask_b32_e32 v109, v220, v111, vcc
	v_cmp_lt_i32_e32 vcc, 21, v187
	v_max3_f32 v66, v70, v108, v109
	v_cndmask_b32_e64 v201, v128, v220, s[70:71]
	v_cndmask_b32_e32 v110, v220, v112, vcc
	v_cmp_lt_i32_e32 vcc, 22, v187
	v_cndmask_b32_e64 v112, v114, v220, s[40:41]
	v_cndmask_b32_e64 v100, v129, v220, s[54:55]
	v_cndmask_b32_e32 v111, v220, v113, vcc
	v_max3_f32 v66, v66, v110, v111
	v_max3_f32 v66, v66, v112, v196
	v_max3_f32 v66, v66, v197, v198
	v_max3_f32 v66, v66, v199, v200
	v_max3_f32 v66, v66, v202, v203
	v_max3_f32 v66, v66, v204, v205
	v_max3_f32 v66, v66, v226, v227
	v_max3_f32 v66, v66, v228, v229
	v_max3_f32 v66, v66, v201, v100
	v_mov_b32_e32 v67, v66
	s_nop 1
	v_permlane32_swap_b32_e32 v67, v66
	s_waitcnt lgkmcnt(0)
	v_max_f32_e32 v67, v67, v67
	v_max_f32_e32 v66, v66, v67
	v_mul_f32_e32 v129, 0x3e38aa3b, v66
	v_add_f32_e32 v66, 0x40c00000, v189
	v_cmp_gt_f32_e32 vcc, v129, v66
	v_mov_b64_e32 v[80:81], v[48:49]
	v_mov_b64_e32 v[78:79], v[46:47]
	v_mov_b64_e32 v[76:77], v[44:45]
	v_mov_b64_e32 v[74:75], v[42:43]
	v_mov_b64_e32 v[72:73], v[40:41]
	v_mov_b64_e32 v[70:71], v[38:39]
	v_mov_b64_e32 v[68:69], v[36:37]
	v_mov_b64_e32 v[66:67], v[34:35]
	s_cbranch_vccz .LBB0_932
	v_cndmask_b32_e32 v190, v189, v129, vcc
	v_sub_f32_e32 v66, v189, v190
	v_exp_f32_e32 v66, v66
	s_nop 0
	v_cndmask_b32_e32 v82, 1.0, v66, vcc
	v_mul_f32_e32 v99, v188, v82
	v_pk_mul_f32 v[80:81], v[48:49], v[82:83] op_sel_hi:[1,0]
	v_pk_mul_f32 v[78:79], v[46:47], v[82:83] op_sel_hi:[1,0]
	v_pk_mul_f32 v[76:77], v[44:45], v[82:83] op_sel_hi:[1,0]
	v_pk_mul_f32 v[74:75], v[42:43], v[82:83] op_sel_hi:[1,0]
	v_pk_mul_f32 v[72:73], v[40:41], v[82:83] op_sel_hi:[1,0]
	v_pk_mul_f32 v[70:71], v[38:39], v[82:83] op_sel_hi:[1,0]
	v_pk_mul_f32 v[68:69], v[36:37], v[82:83] op_sel_hi:[1,0]
	v_pk_mul_f32 v[66:67], v[34:35], v[82:83] op_sel_hi:[1,0]
	v_pk_mul_f32 v[96:97], v[64:65], v[82:83] op_sel_hi:[1,0]
	v_pk_mul_f32 v[94:95], v[62:63], v[82:83] op_sel_hi:[1,0]
	v_pk_mul_f32 v[92:93], v[60:61], v[82:83] op_sel_hi:[1,0]
	v_pk_mul_f32 v[90:91], v[58:59], v[82:83] op_sel_hi:[1,0]
	v_pk_mul_f32 v[88:89], v[56:57], v[82:83] op_sel_hi:[1,0]
	v_pk_mul_f32 v[86:87], v[54:55], v[82:83] op_sel_hi:[1,0]
	v_pk_mul_f32 v[84:85], v[52:53], v[82:83] op_sel_hi:[1,0]
	v_pk_mul_f32 v[82:83], v[50:51], v[82:83] op_sel_hi:[1,0]

.LBB0_934:
	s_andn2_b64 vcc, exec, s[2:3]
	s_cbranch_vccnz .LBB0_940
	s_cmp_lg_u32 s76, 1
	s_cbranch_scc1 .LBB0_939
	v_add3_u32 v102, s23, v170, v173
	s_setprio 1
	ds_read_b128 v[66:69], v102
	ds_read_b128 v[70:73], v102 offset:16
	ds_read_b128 v[74:77], v102 offset:32
	ds_read_b128 v[78:81], v102 offset:48
	s_waitcnt lgkmcnt(3)
	v_mfma_f32_32x32x16_bf16 v[82:97], v[66:69], v[130:133], 0
	ds_read_b128 v[66:69], v102 offset:4608
	ds_read_b128 v[98:101], v102 offset:4624
	s_waitcnt lgkmcnt(4)
	v_mfma_f32_32x32x16_bf16 v[82:97], v[70:73], v[134:137], v[82:97]
	s_waitcnt lgkmcnt(3)
	v_mfma_f32_32x32x16_bf16 v[82:97], v[74:77], v[138:141], v[82:97]
	s_waitcnt lgkmcnt(2)
	v_mfma_f32_32x32x16_bf16 v[82:97], v[78:81], v[142:145], v[82:97]
	s_waitcnt lgkmcnt(1)
	v_mfma_f32_32x32x16_bf16 v[66:81], v[66:69], v[130:133], 0
	s_waitcnt lgkmcnt(0)
	v_mfma_f32_32x32x16_bf16 v[66:81], v[98:101], v[134:137], v[66:81]
	ds_read_b128 v[98:101], v102 offset:4640
	s_waitcnt lgkmcnt(0)
	v_mfma_f32_32x32x16_bf16 v[66:81], v[98:101], v[138:141], v[66:81]
	ds_read_b128 v[98:101], v102 offset:4656
	s_waitcnt lgkmcnt(0)
	v_mfma_f32_32x32x16_bf16 v[66:81], v[98:101], v[142:145], v[66:81]
	s_nop 1
	v_max3_f32 v98, v82, s85, v83
	v_max3_f32 v98, v98, v84, v85
	v_max3_f32 v98, v98, v86, v87
	v_max3_f32 v98, v98, v88, v89
	v_max3_f32 v98, v98, v90, v91
	v_max3_f32 v98, v98, v92, v93
	v_max3_f32 v98, v98, v94, v95
	v_max3_f32 v98, v98, v96, v97
	s_nop 1
	v_max3_f32 v98, v98, v66, v67
	v_max3_f32 v98, v98, v68, v69
	v_max3_f32 v98, v98, v70, v71
	v_max3_f32 v98, v98, v72, v73
	v_max3_f32 v98, v98, v74, v75
	v_max3_f32 v98, v98, v76, v77
	v_max3_f32 v98, v98, v78, v79
	v_max3_f32 v98, v98, v80, v81
	v_mov_b32_e32 v99, v98
	s_nop 1
	v_permlane32_swap_b32_e32 v99, v98
	s_waitcnt lgkmcnt(0)
	v_max_f32_e32 v99, v99, v99
	v_max_f32_e32 v98, v98, v99
	v_mul_f32_e32 v98, 0x3e38aa3b, v98
	v_add_f32_e32 v99, 0x40c00000, v189
	v_cmp_gt_f32_e32 vcc, v98, v99
	s_cbranch_vccz .LBB0_938
	s_nop 0
	v_cndmask_b32_e32 v99, v189, v98, vcc
	v_sub_f32_e32 v98, v189, v99
	v_exp_f32_e32 v98, v98
	v_mov_b32_e32 v189, v99
	v_cndmask_b32_e32 v98, 1.0, v98, vcc
	v_mul_f32_e32 v188, v188, v98
	v_pk_mul_f32 v[48:49], v[48:49], v[98:99] op_sel_hi:[1,0]
	v_pk_mul_f32 v[46:47], v[46:47], v[98:99] op_sel_hi:[1,0]
	v_pk_mul_f32 v[44:45], v[44:45], v[98:99] op_sel_hi:[1,0]
	v_pk_mul_f32 v[42:43], v[42:43], v[98:99] op_sel_hi:[1,0]
	v_pk_mul_f32 v[40:41], v[40:41], v[98:99] op_sel_hi:[1,0]
	v_pk_mul_f32 v[38:39], v[38:39], v[98:99] op_sel_hi:[1,0]
	v_pk_mul_f32 v[36:37], v[36:37], v[98:99] op_sel_hi:[1,0]
	v_pk_mul_f32 v[34:35], v[34:35], v[98:99] op_sel_hi:[1,0]
	v_pk_mul_f32 v[64:65], v[64:65], v[98:99] op_sel_hi:[1,0]
	v_pk_mul_f32 v[62:63], v[62:63], v[98:99] op_sel_hi:[1,0]
	v_pk_mul_f32 v[60:61], v[60:61], v[98:99] op_sel_hi:[1,0]
	v_pk_mul_f32 v[58:59], v[58:59], v[98:99] op_sel_hi:[1,0]
	v_pk_mul_f32 v[56:57], v[56:57], v[98:99] op_sel_hi:[1,0]
	v_pk_mul_f32 v[54:55], v[54:55], v[98:99] op_sel_hi:[1,0]
	v_pk_mul_f32 v[52:53], v[52:53], v[98:99] op_sel_hi:[1,0]
	v_pk_mul_f32 v[50:51], v[50:51], v[98:99] op_sel_hi:[1,0]
